# scans: one operand batch per task (63 steps requested at once) instead of two batches of 32
# speedup vs baseline: 1.0406x; 1.0047x over previous
; __device__ __forceinline__ void s5_scan(const PA& a, int layer, int task, int lane) {
;     const int g = task & 15;
;     const float* sa = (const float*)(a.ws + WS_S5A) + (size_t)(layer * 16 + g) * 256;
;     float* XL = (float*)(a.ws + WS_XLOC) + (size_t)(task * 64) * 128;
;     const float Lr = sa[128 + lane], Li = sa[192 + lane];
;     float xr = 0.f, xi = 0.f;
; #pragma unroll 1
;     for (int c0 = 0; c0 < 64; c0 += 32) {
;         float lr[32], li[32];
; #pragma unroll
;         for (int i = 0; i < 32; ++i) { lr[i] = XL[(c0 + i) * 128 + lane]; li[i] = XL[(c0 + i) * 128 + 64 + lane]; }
; #pragma unroll
;         for (int i = 0; i < 32; ++i) { __hip_atomic_store(XL + (c0 + i) * 128 + lane, xr, __ATOMIC_RELAXED, __HIP_MEMORY_SCOPE_AGENT); __hip_atomic_store(XL + (c0 + i) * 128 + 64 + lane, xi, __ATOMIC_RELAXED, __HIP_MEMORY_SCOPE_AGENT);
;             const float nr = Lr * xr - Li * xi + lr[i], ni = Lr * xi + Li * xr + li[i]; xr = nr; xi = ni; }
;     }
; }
; __global__ void __launch_bounds__(NWAVES * 64, 2) hymba_fwd(Args args) {
;     ...
;               else if (wave == 2) { for (int t2 = vcu; t2 < 32; t2 += G) { s5_scan(pa, layer, t2, lane); ++ndone; } }
.LBB0_557:
	s_lshl_b32 s0, s39, 8
	s_and_b32 s0, s0, 0xf00
	s_or_b32 s62, s0, s38
	v_lshl_add_u64 v[6:7], s[62:63], 2, v[0:1]
	global_load_dword v4, v[6:7], off offset:512
	s_nop 0
	global_load_dword v6, v[6:7], off offset:768
	s_lshl_b32 s0, s39, 6
	s_ashr_i32 s1, s0, 31
	s_lshl_b64 s[0:1], s[0:1], 9
	s_add_u32 s0, s48, s0
	s_addc_u32 s1, s49, s1
	s_mov_b32 s62, 0
	s_mov_b64 s[10:11], s[0:1]
	global_load_dword v8, v2, s[10:11]
	global_load_dword v9, v2, s[10:11] offset:256
	global_load_dword v10, v2, s[10:11] offset:512
	global_load_dword v11, v2, s[10:11] offset:768
	global_load_dword v12, v2, s[10:11] offset:1024
	global_load_dword v13, v2, s[10:11] offset:1280
	global_load_dword v14, v2, s[10:11] offset:1536
	global_load_dword v15, v2, s[10:11] offset:1792
	global_load_dword v16, v2, s[10:11] offset:2048
	global_load_dword v17, v2, s[10:11] offset:2304
	global_load_dword v18, v2, s[10:11] offset:2560
	global_load_dword v19, v2, s[10:11] offset:2816
	global_load_dword v20, v2, s[10:11] offset:3072
	global_load_dword v21, v2, s[10:11] offset:3328
	global_load_dword v22, v2, s[10:11] offset:3584
	global_load_dword v23, v2, s[10:11] offset:3840
	s_add_u32 s10, s10, 0x1000
	s_addc_u32 s11, s11, 0
	global_load_dword v24, v2, s[10:11]
	global_load_dword v25, v2, s[10:11] offset:256
	global_load_dword v26, v2, s[10:11] offset:512
	global_load_dword v27, v2, s[10:11] offset:768
	global_load_dword v28, v2, s[10:11] offset:1024
	global_load_dword v29, v2, s[10:11] offset:1280
	global_load_dword v30, v2, s[10:11] offset:1536
	global_load_dword v31, v2, s[10:11] offset:1792
	global_load_dword v32, v2, s[10:11] offset:2048
	global_load_dword v33, v2, s[10:11] offset:2304
	global_load_dword v34, v2, s[10:11] offset:2560
	global_load_dword v35, v2, s[10:11] offset:2816
	global_load_dword v36, v2, s[10:11] offset:3072
	global_load_dword v37, v2, s[10:11] offset:3328
	global_load_dword v38, v2, s[10:11] offset:3584
	global_load_dword v39, v2, s[10:11] offset:3840
	s_add_u32 s10, s10, 0x1000
	s_addc_u32 s11, s11, 0
	global_load_dword v40, v2, s[10:11]
	global_load_dword v41, v2, s[10:11] offset:256
	global_load_dword v42, v2, s[10:11] offset:512
	global_load_dword v43, v2, s[10:11] offset:768
	global_load_dword v44, v2, s[10:11] offset:1024
	global_load_dword v45, v2, s[10:11] offset:1280
	global_load_dword v46, v2, s[10:11] offset:1536
	global_load_dword v47, v2, s[10:11] offset:1792
	global_load_dword v48, v2, s[10:11] offset:2048
	global_load_dword v49, v2, s[10:11] offset:2304
	global_load_dword v50, v2, s[10:11] offset:2560
	global_load_dword v51, v2, s[10:11] offset:2816
	global_load_dword v52, v2, s[10:11] offset:3072
	global_load_dword v53, v2, s[10:11] offset:3328
	global_load_dword v54, v2, s[10:11] offset:3584
	global_load_dword v55, v2, s[10:11] offset:3840
	s_add_u32 s10, s10, 0x1000
	s_addc_u32 s11, s11, 0
	global_load_dword v56, v2, s[10:11]
	global_load_dword v57, v2, s[10:11] offset:256
	global_load_dword v58, v2, s[10:11] offset:512
	global_load_dword v59, v2, s[10:11] offset:768
	global_load_dword v60, v2, s[10:11] offset:1024
	global_load_dword v61, v2, s[10:11] offset:1280
	global_load_dword v62, v2, s[10:11] offset:1536
	global_load_dword v63, v2, s[10:11] offset:1792
	global_load_dword v64, v2, s[10:11] offset:2048
	global_load_dword v65, v2, s[10:11] offset:2304
	global_load_dword v66, v2, s[10:11] offset:2560
	global_load_dword v67, v2, s[10:11] offset:2816
	global_load_dword v68, v2, s[10:11] offset:3072
	global_load_dword v69, v2, s[10:11] offset:3328
	global_load_dword v70, v2, s[10:11] offset:3584
	global_load_dword v71, v2, s[10:11] offset:3840
	s_add_u32 s10, s10, 0x1000
	s_addc_u32 s11, s11, 0
	global_load_dword v72, v2, s[10:11]
	global_load_dword v73, v2, s[10:11] offset:256
	global_load_dword v74, v2, s[10:11] offset:512
	global_load_dword v75, v2, s[10:11] offset:768
	global_load_dword v76, v2, s[10:11] offset:1024
	global_load_dword v77, v2, s[10:11] offset:1280
	global_load_dword v78, v2, s[10:11] offset:1536
	global_load_dword v79, v2, s[10:11] offset:1792
	global_load_dword v80, v2, s[10:11] offset:2048
	global_load_dword v81, v2, s[10:11] offset:2304
	global_load_dword v82, v2, s[10:11] offset:2560
	global_load_dword v83, v2, s[10:11] offset:2816
	global_load_dword v84, v2, s[10:11] offset:3072
	global_load_dword v85, v2, s[10:11] offset:3328
	global_load_dword v86, v2, s[10:11] offset:3584
	global_load_dword v87, v2, s[10:11] offset:3840
	s_add_u32 s10, s10, 0x1000
	s_addc_u32 s11, s11, 0
	global_load_dword v88, v2, s[10:11]
	global_load_dword v89, v2, s[10:11] offset:256
	global_load_dword v90, v2, s[10:11] offset:512
	global_load_dword v91, v2, s[10:11] offset:768
	global_load_dword v92, v2, s[10:11] offset:1024
	global_load_dword v93, v2, s[10:11] offset:1280
	global_load_dword v94, v2, s[10:11] offset:1536
	global_load_dword v95, v2, s[10:11] offset:1792
	global_load_dword v97, v2, s[10:11] offset:2048
	global_load_dword v98, v2, s[10:11] offset:2304
	global_load_dword v99, v2, s[10:11] offset:2560
	global_load_dword v100, v2, s[10:11] offset:2816
	global_load_dword v101, v2, s[10:11] offset:3072
	global_load_dword v102, v2, s[10:11] offset:3328
	global_load_dword v103, v2, s[10:11] offset:3584
	global_load_dword v104, v2, s[10:11] offset:3840
	s_add_u32 s10, s10, 0x1000
	s_addc_u32 s11, s11, 0
	global_load_dword v105, v2, s[10:11]
	global_load_dword v106, v2, s[10:11] offset:256
	global_load_dword v107, v2, s[10:11] offset:512
	global_load_dword v108, v2, s[10:11] offset:768
	global_load_dword v109, v2, s[10:11] offset:1024
	global_load_dword v110, v2, s[10:11] offset:1280
	global_load_dword v111, v2, s[10:11] offset:1536
	global_load_dword v112, v2, s[10:11] offset:1792
	global_load_dword v113, v2, s[10:11] offset:2048
	global_load_dword v114, v2, s[10:11] offset:2304
	global_load_dword v115, v2, s[10:11] offset:2560
	global_load_dword v116, v2, s[10:11] offset:2816
	global_load_dword v117, v2, s[10:11] offset:3072
	global_load_dword v118, v2, s[10:11] offset:3328
	global_load_dword v119, v2, s[10:11] offset:3584
	global_load_dword v120, v2, s[10:11] offset:3840
	s_add_u32 s10, s10, 0x1000
	s_addc_u32 s11, s11, 0
	global_load_dword v121, v2, s[10:11]
	global_load_dword v122, v2, s[10:11] offset:256
	global_load_dword v123, v2, s[10:11] offset:512
	global_load_dword v124, v2, s[10:11] offset:768
	global_load_dword v125, v2, s[10:11] offset:1024
	global_load_dword v126, v2, s[10:11] offset:1280
	global_load_dword v127, v2, s[10:11] offset:1536
	global_load_dword v128, v2, s[10:11] offset:1792
	global_load_dword v129, v2, s[10:11] offset:2048
	global_load_dword v130, v2, s[10:11] offset:2304
	global_load_dword v131, v2, s[10:11] offset:2560
	global_load_dword v132, v2, s[10:11] offset:2816
	global_load_dword v133, v2, s[10:11] offset:3072
	global_load_dword v134, v2, s[10:11] offset:3328
	v_mov_b32_e32 v135, 0
	v_mov_b32_e32 v136, 0
	s_mov_b64 s[10:11], s[0:1]
	global_store_dword v2, v135, s[10:11] sc1
	global_store_dword v2, v136, s[10:11] offset:256 sc1
	s_waitcnt vmcnt(63)
; __device__ __forceinline__ void s5_scan(const PA& a, int layer, int task, int lane) {
;     ...
;         for (int i = 0; i < 32; ++i) { __hip_atomic_store(XL + (c0 + i) * 128 + lane, xr, __ATOMIC_RELAXED, __HIP_MEMORY_SCOPE_AGENT); __hip_atomic_store(XL + (c0 + i) * 128 + 64 + lane, xi, __ATOMIC_RELAXED, __HIP_MEMORY_SCOPE_AGENT);
;             const float nr = Lr * xr - Li * xi + lr[i], ni = Lr * xi + Li * xr + li[i]; xr = nr; xi = ni; }
	v_mul_f32_e32 v5, v6, v136
	v_mul_f32_e32 v7, v6, v135
	v_fma_f32 v5, v4, v135, -v5
	v_fma_f32 v7, v4, v136, v7
	v_add_f32_e32 v137, v5, v8
	v_add_f32_e32 v138, v7, v9
	global_store_dword v2, v137, s[10:11] offset:512 sc1
	global_store_dword v2, v138, s[10:11] offset:768 sc1
	s_waitcnt vmcnt(63)
	v_mul_f32_e32 v5, v6, v138
	v_mul_f32_e32 v7, v6, v137
	v_fma_f32 v5, v4, v137, -v5
	v_fma_f32 v7, v4, v138, v7
	v_add_f32_e32 v135, v5, v10
	v_add_f32_e32 v136, v7, v11
	global_store_dword v2, v135, s[10:11] offset:1024 sc1
	global_store_dword v2, v136, s[10:11] offset:1280 sc1
	s_waitcnt vmcnt(63)
	v_mul_f32_e32 v5, v6, v136
	v_mul_f32_e32 v7, v6, v135
	v_fma_f32 v5, v4, v135, -v5
	v_fma_f32 v7, v4, v136, v7
	v_add_f32_e32 v137, v5, v12
	v_add_f32_e32 v138, v7, v13
	global_store_dword v2, v137, s[10:11] offset:1536 sc1
	global_store_dword v2, v138, s[10:11] offset:1792 sc1
	s_waitcnt vmcnt(63)
	v_mul_f32_e32 v5, v6, v138
	v_mul_f32_e32 v7, v6, v137
	v_fma_f32 v5, v4, v137, -v5
	v_fma_f32 v7, v4, v138, v7
	v_add_f32_e32 v135, v5, v14
	v_add_f32_e32 v136, v7, v15
	global_store_dword v2, v135, s[10:11] offset:2048 sc1
	global_store_dword v2, v136, s[10:11] offset:2304 sc1
	s_waitcnt vmcnt(63)
	v_mul_f32_e32 v5, v6, v136
	v_mul_f32_e32 v7, v6, v135
	v_fma_f32 v5, v4, v135, -v5
	v_fma_f32 v7, v4, v136, v7
	v_add_f32_e32 v137, v5, v16
	v_add_f32_e32 v138, v7, v17
	global_store_dword v2, v137, s[10:11] offset:2560 sc1
	global_store_dword v2, v138, s[10:11] offset:2816 sc1
	s_waitcnt vmcnt(63)
	v_mul_f32_e32 v5, v6, v138
	v_mul_f32_e32 v7, v6, v137
	v_fma_f32 v5, v4, v137, -v5
	v_fma_f32 v7, v4, v138, v7
	v_add_f32_e32 v135, v5, v18
	v_add_f32_e32 v136, v7, v19
	global_store_dword v2, v135, s[10:11] offset:3072 sc1
	global_store_dword v2, v136, s[10:11] offset:3328 sc1
	s_waitcnt vmcnt(63)
	v_mul_f32_e32 v5, v6, v136
	v_mul_f32_e32 v7, v6, v135
	v_fma_f32 v5, v4, v135, -v5
	v_fma_f32 v7, v4, v136, v7
	v_add_f32_e32 v137, v5, v20
	v_add_f32_e32 v138, v7, v21
	global_store_dword v2, v137, s[10:11] offset:3584 sc1
	global_store_dword v2, v138, s[10:11] offset:3840 sc1
	s_waitcnt vmcnt(63)
	v_mul_f32_e32 v5, v6, v138
	v_mul_f32_e32 v7, v6, v137
	v_fma_f32 v5, v4, v137, -v5
	v_fma_f32 v7, v4, v138, v7
	v_add_f32_e32 v135, v5, v22
	v_add_f32_e32 v136, v7, v23
	s_add_u32 s10, s10, 0x1000
	s_addc_u32 s11, s11, 0
	global_store_dword v2, v135, s[10:11] sc1
	global_store_dword v2, v136, s[10:11] offset:256 sc1
	s_waitcnt vmcnt(63)
	v_mul_f32_e32 v5, v6, v136
	v_mul_f32_e32 v7, v6, v135
	v_fma_f32 v5, v4, v135, -v5
	v_fma_f32 v7, v4, v136, v7
	v_add_f32_e32 v137, v5, v24
	v_add_f32_e32 v138, v7, v25
	global_store_dword v2, v137, s[10:11] offset:512 sc1
	global_store_dword v2, v138, s[10:11] offset:768 sc1
	s_waitcnt vmcnt(63)
	v_mul_f32_e32 v5, v6, v138
	v_mul_f32_e32 v7, v6, v137
	v_fma_f32 v5, v4, v137, -v5
	v_fma_f32 v7, v4, v138, v7
	v_add_f32_e32 v135, v5, v26
	v_add_f32_e32 v136, v7, v27
	global_store_dword v2, v135, s[10:11] offset:1024 sc1
	global_store_dword v2, v136, s[10:11] offset:1280 sc1
	s_waitcnt vmcnt(63)
	v_mul_f32_e32 v5, v6, v136
	v_mul_f32_e32 v7, v6, v135
	v_fma_f32 v5, v4, v135, -v5
	v_fma_f32 v7, v4, v136, v7
	v_add_f32_e32 v137, v5, v28
	v_add_f32_e32 v138, v7, v29
	global_store_dword v2, v137, s[10:11] offset:1536 sc1
	global_store_dword v2, v138, s[10:11] offset:1792 sc1
	s_waitcnt vmcnt(63)
	v_mul_f32_e32 v5, v6, v138
	v_mul_f32_e32 v7, v6, v137
	v_fma_f32 v5, v4, v137, -v5
	v_fma_f32 v7, v4, v138, v7
	v_add_f32_e32 v135, v5, v30
	v_add_f32_e32 v136, v7, v31
	global_store_dword v2, v135, s[10:11] offset:2048 sc1
	global_store_dword v2, v136, s[10:11] offset:2304 sc1
	s_waitcnt vmcnt(63)
	v_mul_f32_e32 v5, v6, v136
	v_mul_f32_e32 v7, v6, v135
	v_fma_f32 v5, v4, v135, -v5
	v_fma_f32 v7, v4, v136, v7
	v_add_f32_e32 v137, v5, v32
	v_add_f32_e32 v138, v7, v33
	global_store_dword v2, v137, s[10:11] offset:2560 sc1
	global_store_dword v2, v138, s[10:11] offset:2816 sc1
	s_waitcnt vmcnt(63)
	v_mul_f32_e32 v5, v6, v138
	v_mul_f32_e32 v7, v6, v137
	v_fma_f32 v5, v4, v137, -v5
	v_fma_f32 v7, v4, v138, v7
	v_add_f32_e32 v135, v5, v34
	v_add_f32_e32 v136, v7, v35
	global_store_dword v2, v135, s[10:11] offset:3072 sc1
	global_store_dword v2, v136, s[10:11] offset:3328 sc1
	s_waitcnt vmcnt(63)
	v_mul_f32_e32 v5, v6, v136
	v_mul_f32_e32 v7, v6, v135
	v_fma_f32 v5, v4, v135, -v5
	v_fma_f32 v7, v4, v136, v7
	v_add_f32_e32 v137, v5, v36
	v_add_f32_e32 v138, v7, v37
	global_store_dword v2, v137, s[10:11] offset:3584 sc1
	global_store_dword v2, v138, s[10:11] offset:3840 sc1
	s_waitcnt vmcnt(63)
	v_mul_f32_e32 v5, v6, v138
	v_mul_f32_e32 v7, v6, v137
	v_fma_f32 v5, v4, v137, -v5
	v_fma_f32 v7, v4, v138, v7
	v_add_f32_e32 v135, v5, v38
	v_add_f32_e32 v136, v7, v39
	s_add_u32 s10, s10, 0x1000
	s_addc_u32 s11, s11, 0
	global_store_dword v2, v135, s[10:11] sc1
	global_store_dword v2, v136, s[10:11] offset:256 sc1
	s_waitcnt vmcnt(63)
	v_mul_f32_e32 v5, v6, v136
	v_mul_f32_e32 v7, v6, v135
	v_fma_f32 v5, v4, v135, -v5
	v_fma_f32 v7, v4, v136, v7
	v_add_f32_e32 v137, v5, v40
	v_add_f32_e32 v138, v7, v41
	global_store_dword v2, v137, s[10:11] offset:512 sc1
	global_store_dword v2, v138, s[10:11] offset:768 sc1
	s_waitcnt vmcnt(63)
	v_mul_f32_e32 v5, v6, v138
	v_mul_f32_e32 v7, v6, v137
	v_fma_f32 v5, v4, v137, -v5
	v_fma_f32 v7, v4, v138, v7
	v_add_f32_e32 v135, v5, v42
	v_add_f32_e32 v136, v7, v43
	global_store_dword v2, v135, s[10:11] offset:1024 sc1
	global_store_dword v2, v136, s[10:11] offset:1280 sc1
	s_waitcnt vmcnt(63)
; __device__ __forceinline__ void s5_scan(const PA& a, int layer, int task, int lane) {
;     ...
;         for (int i = 0; i < 32; ++i) { __hip_atomic_store(XL + (c0 + i) * 128 + lane, xr, __ATOMIC_RELAXED, __HIP_MEMORY_SCOPE_AGENT); __hip_atomic_store(XL + (c0 + i) * 128 + 64 + lane, xi, __ATOMIC_RELAXED, __HIP_MEMORY_SCOPE_AGENT);
;             const float nr = Lr * xr - Li * xi + lr[i], ni = Lr * xi + Li * xr + li[i]; xr = nr; xi = ni; }
	v_mul_f32_e32 v5, v6, v136
	v_mul_f32_e32 v7, v6, v135
	v_fma_f32 v5, v4, v135, -v5
	v_fma_f32 v7, v4, v136, v7
	v_add_f32_e32 v137, v5, v44
	v_add_f32_e32 v138, v7, v45
	global_store_dword v2, v137, s[10:11] offset:1536 sc1
	global_store_dword v2, v138, s[10:11] offset:1792 sc1
	s_waitcnt vmcnt(63)
	v_mul_f32_e32 v5, v6, v138
	v_mul_f32_e32 v7, v6, v137
	v_fma_f32 v5, v4, v137, -v5
	v_fma_f32 v7, v4, v138, v7
	v_add_f32_e32 v135, v5, v46
	v_add_f32_e32 v136, v7, v47
	global_store_dword v2, v135, s[10:11] offset:2048 sc1
	global_store_dword v2, v136, s[10:11] offset:2304 sc1
	s_waitcnt vmcnt(63)
	v_mul_f32_e32 v5, v6, v136
	v_mul_f32_e32 v7, v6, v135
	v_fma_f32 v5, v4, v135, -v5
	v_fma_f32 v7, v4, v136, v7
	v_add_f32_e32 v137, v5, v48
	v_add_f32_e32 v138, v7, v49
	global_store_dword v2, v137, s[10:11] offset:2560 sc1
	global_store_dword v2, v138, s[10:11] offset:2816 sc1
	s_waitcnt vmcnt(63)
	v_mul_f32_e32 v5, v6, v138
	v_mul_f32_e32 v7, v6, v137
	v_fma_f32 v5, v4, v137, -v5
	v_fma_f32 v7, v4, v138, v7
	v_add_f32_e32 v135, v5, v50
	v_add_f32_e32 v136, v7, v51
	global_store_dword v2, v135, s[10:11] offset:3072 sc1
	global_store_dword v2, v136, s[10:11] offset:3328 sc1
	s_waitcnt vmcnt(63)
	v_mul_f32_e32 v5, v6, v136
	v_mul_f32_e32 v7, v6, v135
	v_fma_f32 v5, v4, v135, -v5
	v_fma_f32 v7, v4, v136, v7
	v_add_f32_e32 v137, v5, v52
	v_add_f32_e32 v138, v7, v53
	global_store_dword v2, v137, s[10:11] offset:3584 sc1
	global_store_dword v2, v138, s[10:11] offset:3840 sc1
	s_waitcnt vmcnt(63)
	v_mul_f32_e32 v5, v6, v138
	v_mul_f32_e32 v7, v6, v137
	v_fma_f32 v5, v4, v137, -v5
	v_fma_f32 v7, v4, v138, v7
	v_add_f32_e32 v135, v5, v54
	v_add_f32_e32 v136, v7, v55
	s_add_u32 s10, s10, 0x1000
	s_addc_u32 s11, s11, 0
	global_store_dword v2, v135, s[10:11] sc1
	global_store_dword v2, v136, s[10:11] offset:256 sc1
	s_waitcnt vmcnt(63)
	v_mul_f32_e32 v5, v6, v136
	v_mul_f32_e32 v7, v6, v135
	v_fma_f32 v5, v4, v135, -v5
	v_fma_f32 v7, v4, v136, v7
	v_add_f32_e32 v137, v5, v56
	v_add_f32_e32 v138, v7, v57
	global_store_dword v2, v137, s[10:11] offset:512 sc1
	global_store_dword v2, v138, s[10:11] offset:768 sc1
	s_waitcnt vmcnt(63)
	v_mul_f32_e32 v5, v6, v138
	v_mul_f32_e32 v7, v6, v137
	v_fma_f32 v5, v4, v137, -v5
	v_fma_f32 v7, v4, v138, v7
	v_add_f32_e32 v135, v5, v58
	v_add_f32_e32 v136, v7, v59
	global_store_dword v2, v135, s[10:11] offset:1024 sc1
	global_store_dword v2, v136, s[10:11] offset:1280 sc1
	s_waitcnt vmcnt(63)
	v_mul_f32_e32 v5, v6, v136
	v_mul_f32_e32 v7, v6, v135
	v_fma_f32 v5, v4, v135, -v5
	v_fma_f32 v7, v4, v136, v7
	v_add_f32_e32 v137, v5, v60
	v_add_f32_e32 v138, v7, v61
	global_store_dword v2, v137, s[10:11] offset:1536 sc1
	global_store_dword v2, v138, s[10:11] offset:1792 sc1
	s_waitcnt vmcnt(63)
	v_mul_f32_e32 v5, v6, v138
	v_mul_f32_e32 v7, v6, v137
	v_fma_f32 v5, v4, v137, -v5
	v_fma_f32 v7, v4, v138, v7
	v_add_f32_e32 v135, v5, v62
	v_add_f32_e32 v136, v7, v63
	global_store_dword v2, v135, s[10:11] offset:2048 sc1
	global_store_dword v2, v136, s[10:11] offset:2304 sc1
	s_waitcnt vmcnt(63)
	v_mul_f32_e32 v5, v6, v136
	v_mul_f32_e32 v7, v6, v135
	v_fma_f32 v5, v4, v135, -v5
	v_fma_f32 v7, v4, v136, v7
	v_add_f32_e32 v137, v5, v64
	v_add_f32_e32 v138, v7, v65
	global_store_dword v2, v137, s[10:11] offset:2560 sc1
	global_store_dword v2, v138, s[10:11] offset:2816 sc1
	s_waitcnt vmcnt(63)
	v_mul_f32_e32 v5, v6, v138
	v_mul_f32_e32 v7, v6, v137
	v_fma_f32 v5, v4, v137, -v5
	v_fma_f32 v7, v4, v138, v7
	v_add_f32_e32 v135, v5, v66
	v_add_f32_e32 v136, v7, v67
	global_store_dword v2, v135, s[10:11] offset:3072 sc1
	global_store_dword v2, v136, s[10:11] offset:3328 sc1
	s_waitcnt vmcnt(63)
	v_mul_f32_e32 v5, v6, v136
	v_mul_f32_e32 v7, v6, v135
	v_fma_f32 v5, v4, v135, -v5
	v_fma_f32 v7, v4, v136, v7
	v_add_f32_e32 v137, v5, v68
	v_add_f32_e32 v138, v7, v69
	global_store_dword v2, v137, s[10:11] offset:3584 sc1
	global_store_dword v2, v138, s[10:11] offset:3840 sc1
	s_waitcnt vmcnt(63)
	v_mul_f32_e32 v5, v6, v138
	v_mul_f32_e32 v7, v6, v137
	v_fma_f32 v5, v4, v137, -v5
	v_fma_f32 v7, v4, v138, v7
	v_add_f32_e32 v135, v5, v70
	v_add_f32_e32 v136, v7, v71
	s_add_u32 s10, s10, 0x1000
	s_addc_u32 s11, s11, 0
	global_store_dword v2, v135, s[10:11] sc1
	global_store_dword v2, v136, s[10:11] offset:256 sc1
	v_mul_f32_e32 v5, v6, v136
	v_mul_f32_e32 v7, v6, v135
	v_fma_f32 v5, v4, v135, -v5
	v_fma_f32 v7, v4, v136, v7
	v_add_f32_e32 v137, v5, v72
	v_add_f32_e32 v138, v7, v73
	global_store_dword v2, v137, s[10:11] offset:512 sc1
	global_store_dword v2, v138, s[10:11] offset:768 sc1
	v_mul_f32_e32 v5, v6, v138
	v_mul_f32_e32 v7, v6, v137
	v_fma_f32 v5, v4, v137, -v5
	v_fma_f32 v7, v4, v138, v7
	v_add_f32_e32 v135, v5, v74
	v_add_f32_e32 v136, v7, v75
	global_store_dword v2, v135, s[10:11] offset:1024 sc1
	global_store_dword v2, v136, s[10:11] offset:1280 sc1
	v_mul_f32_e32 v5, v6, v136
	v_mul_f32_e32 v7, v6, v135
	v_fma_f32 v5, v4, v135, -v5
	v_fma_f32 v7, v4, v136, v7
	v_add_f32_e32 v137, v5, v76
	v_add_f32_e32 v138, v7, v77
	global_store_dword v2, v137, s[10:11] offset:1536 sc1
	global_store_dword v2, v138, s[10:11] offset:1792 sc1
	v_mul_f32_e32 v5, v6, v138
	v_mul_f32_e32 v7, v6, v137
	v_fma_f32 v5, v4, v137, -v5
	v_fma_f32 v7, v4, v138, v7
	v_add_f32_e32 v135, v5, v78
	v_add_f32_e32 v136, v7, v79
	global_store_dword v2, v135, s[10:11] offset:2048 sc1
	global_store_dword v2, v136, s[10:11] offset:2304 sc1
	v_mul_f32_e32 v5, v6, v136
	v_mul_f32_e32 v7, v6, v135
	v_fma_f32 v5, v4, v135, -v5
	v_fma_f32 v7, v4, v136, v7
	v_add_f32_e32 v137, v5, v80
	v_add_f32_e32 v138, v7, v81
	global_store_dword v2, v137, s[10:11] offset:2560 sc1
; __device__ __forceinline__ void s5_scan(const PA& a, int layer, int task, int lane) {
;     ...
;         for (int i = 0; i < 32; ++i) { __hip_atomic_store(XL + (c0 + i) * 128 + lane, xr, __ATOMIC_RELAXED, __HIP_MEMORY_SCOPE_AGENT); __hip_atomic_store(XL + (c0 + i) * 128 + 64 + lane, xi, __ATOMIC_RELAXED, __HIP_MEMORY_SCOPE_AGENT);
;             const float nr = Lr * xr - Li * xi + lr[i], ni = Lr * xi + Li * xr + li[i]; xr = nr; xi = ni; }
	global_store_dword v2, v138, s[10:11] offset:2816 sc1
	v_mul_f32_e32 v5, v6, v138
	v_mul_f32_e32 v7, v6, v137
	v_fma_f32 v5, v4, v137, -v5
	v_fma_f32 v7, v4, v138, v7
	v_add_f32_e32 v135, v5, v82
	v_add_f32_e32 v136, v7, v83
	global_store_dword v2, v135, s[10:11] offset:3072 sc1
	global_store_dword v2, v136, s[10:11] offset:3328 sc1
	v_mul_f32_e32 v5, v6, v136
	v_mul_f32_e32 v7, v6, v135
	v_fma_f32 v5, v4, v135, -v5
	v_fma_f32 v7, v4, v136, v7
	v_add_f32_e32 v137, v5, v84
	v_add_f32_e32 v138, v7, v85
	global_store_dword v2, v137, s[10:11] offset:3584 sc1
	global_store_dword v2, v138, s[10:11] offset:3840 sc1
	v_mul_f32_e32 v5, v6, v138
	v_mul_f32_e32 v7, v6, v137
	v_fma_f32 v5, v4, v137, -v5
	v_fma_f32 v7, v4, v138, v7
	v_add_f32_e32 v135, v5, v86
	v_add_f32_e32 v136, v7, v87
	s_add_u32 s10, s10, 0x1000
	s_addc_u32 s11, s11, 0
	global_store_dword v2, v135, s[10:11] sc1
	global_store_dword v2, v136, s[10:11] offset:256 sc1
	v_mul_f32_e32 v5, v6, v136
	v_mul_f32_e32 v7, v6, v135
	v_fma_f32 v5, v4, v135, -v5
	v_fma_f32 v7, v4, v136, v7
	v_add_f32_e32 v137, v5, v88
	v_add_f32_e32 v138, v7, v89
	global_store_dword v2, v137, s[10:11] offset:512 sc1
	global_store_dword v2, v138, s[10:11] offset:768 sc1
	v_mul_f32_e32 v5, v6, v138
	v_mul_f32_e32 v7, v6, v137
	v_fma_f32 v5, v4, v137, -v5
	v_fma_f32 v7, v4, v138, v7
	v_add_f32_e32 v135, v5, v90
	v_add_f32_e32 v136, v7, v91
	global_store_dword v2, v135, s[10:11] offset:1024 sc1
	global_store_dword v2, v136, s[10:11] offset:1280 sc1
	v_mul_f32_e32 v5, v6, v136
	v_mul_f32_e32 v7, v6, v135
	v_fma_f32 v5, v4, v135, -v5
	v_fma_f32 v7, v4, v136, v7
	v_add_f32_e32 v137, v5, v92
	v_add_f32_e32 v138, v7, v93
	global_store_dword v2, v137, s[10:11] offset:1536 sc1
	global_store_dword v2, v138, s[10:11] offset:1792 sc1
	v_mul_f32_e32 v5, v6, v138
	v_mul_f32_e32 v7, v6, v137
	v_fma_f32 v5, v4, v137, -v5
	v_fma_f32 v7, v4, v138, v7
	v_add_f32_e32 v135, v5, v94
	v_add_f32_e32 v136, v7, v95
	global_store_dword v2, v135, s[10:11] offset:2048 sc1
	global_store_dword v2, v136, s[10:11] offset:2304 sc1
	v_mul_f32_e32 v5, v6, v136
	v_mul_f32_e32 v7, v6, v135
	v_fma_f32 v5, v4, v135, -v5
	v_fma_f32 v7, v4, v136, v7
	v_add_f32_e32 v137, v5, v97
	v_add_f32_e32 v138, v7, v98
	global_store_dword v2, v137, s[10:11] offset:2560 sc1
	global_store_dword v2, v138, s[10:11] offset:2816 sc1
	v_mul_f32_e32 v5, v6, v138
	v_mul_f32_e32 v7, v6, v137
	v_fma_f32 v5, v4, v137, -v5
	v_fma_f32 v7, v4, v138, v7
	v_add_f32_e32 v135, v5, v99
	v_add_f32_e32 v136, v7, v100
	global_store_dword v2, v135, s[10:11] offset:3072 sc1
	global_store_dword v2, v136, s[10:11] offset:3328 sc1
	v_mul_f32_e32 v5, v6, v136
	v_mul_f32_e32 v7, v6, v135
	v_fma_f32 v5, v4, v135, -v5
	v_fma_f32 v7, v4, v136, v7
	v_add_f32_e32 v137, v5, v101
	v_add_f32_e32 v138, v7, v102
	global_store_dword v2, v137, s[10:11] offset:3584 sc1
	global_store_dword v2, v138, s[10:11] offset:3840 sc1
	v_mul_f32_e32 v5, v6, v138
	v_mul_f32_e32 v7, v6, v137
	v_fma_f32 v5, v4, v137, -v5
	v_fma_f32 v7, v4, v138, v7
	v_add_f32_e32 v135, v5, v103
	v_add_f32_e32 v136, v7, v104
	s_add_u32 s10, s10, 0x1000
	s_addc_u32 s11, s11, 0
	global_store_dword v2, v135, s[10:11] sc1
	global_store_dword v2, v136, s[10:11] offset:256 sc1
	v_mul_f32_e32 v5, v6, v136
	v_mul_f32_e32 v7, v6, v135
	v_fma_f32 v5, v4, v135, -v5
	v_fma_f32 v7, v4, v136, v7
	v_add_f32_e32 v137, v5, v105
	v_add_f32_e32 v138, v7, v106
	global_store_dword v2, v137, s[10:11] offset:512 sc1
	global_store_dword v2, v138, s[10:11] offset:768 sc1
	v_mul_f32_e32 v5, v6, v138
	v_mul_f32_e32 v7, v6, v137
	v_fma_f32 v5, v4, v137, -v5
	v_fma_f32 v7, v4, v138, v7
	v_add_f32_e32 v135, v5, v107
	v_add_f32_e32 v136, v7, v108
	global_store_dword v2, v135, s[10:11] offset:1024 sc1
	global_store_dword v2, v136, s[10:11] offset:1280 sc1
	v_mul_f32_e32 v5, v6, v136
	v_mul_f32_e32 v7, v6, v135
	v_fma_f32 v5, v4, v135, -v5
; __device__ __forceinline__ void s5_scan(const PA& a, int layer, int task, int lane) {
;     ...
;         for (int i = 0; i < 32; ++i) { __hip_atomic_store(XL + (c0 + i) * 128 + lane, xr, __ATOMIC_RELAXED, __HIP_MEMORY_SCOPE_AGENT); __hip_atomic_store(XL + (c0 + i) * 128 + 64 + lane, xi, __ATOMIC_RELAXED, __HIP_MEMORY_SCOPE_AGENT);
;             const float nr = Lr * xr - Li * xi + lr[i], ni = Lr * xi + Li * xr + li[i]; xr = nr; xi = ni; }
; __global__ void __launch_bounds__(NWAVES * 64, 2) hymba_fwd(Args args) {
;     ...
;               else if (wave == 2) { for (int t2 = vcu; t2 < 32; t2 += G) { s5_scan(pa, layer, t2, lane); ++ndone; } }
	v_fma_f32 v7, v4, v136, v7
	v_add_f32_e32 v137, v5, v109
	v_add_f32_e32 v138, v7, v110
	global_store_dword v2, v137, s[10:11] offset:1536 sc1
	global_store_dword v2, v138, s[10:11] offset:1792 sc1
	v_mul_f32_e32 v5, v6, v138
	v_mul_f32_e32 v7, v6, v137
	v_fma_f32 v5, v4, v137, -v5
	v_fma_f32 v7, v4, v138, v7
	v_add_f32_e32 v135, v5, v111
	v_add_f32_e32 v136, v7, v112
	global_store_dword v2, v135, s[10:11] offset:2048 sc1
	global_store_dword v2, v136, s[10:11] offset:2304 sc1
	v_mul_f32_e32 v5, v6, v136
	v_mul_f32_e32 v7, v6, v135
	v_fma_f32 v5, v4, v135, -v5
	v_fma_f32 v7, v4, v136, v7
	v_add_f32_e32 v137, v5, v113
	v_add_f32_e32 v138, v7, v114
	global_store_dword v2, v137, s[10:11] offset:2560 sc1
	global_store_dword v2, v138, s[10:11] offset:2816 sc1
	v_mul_f32_e32 v5, v6, v138
	v_mul_f32_e32 v7, v6, v137
	v_fma_f32 v5, v4, v137, -v5
	v_fma_f32 v7, v4, v138, v7
	v_add_f32_e32 v135, v5, v115
	v_add_f32_e32 v136, v7, v116
	global_store_dword v2, v135, s[10:11] offset:3072 sc1
	global_store_dword v2, v136, s[10:11] offset:3328 sc1
	v_mul_f32_e32 v5, v6, v136
	v_mul_f32_e32 v7, v6, v135
	v_fma_f32 v5, v4, v135, -v5
	v_fma_f32 v7, v4, v136, v7
	v_add_f32_e32 v137, v5, v117
	v_add_f32_e32 v138, v7, v118
	global_store_dword v2, v137, s[10:11] offset:3584 sc1
	global_store_dword v2, v138, s[10:11] offset:3840 sc1
	v_mul_f32_e32 v5, v6, v138
	v_mul_f32_e32 v7, v6, v137
	v_fma_f32 v5, v4, v137, -v5
	v_fma_f32 v7, v4, v138, v7
	v_add_f32_e32 v135, v5, v119
	v_add_f32_e32 v136, v7, v120
	s_add_u32 s10, s10, 0x1000
	s_addc_u32 s11, s11, 0
	global_store_dword v2, v135, s[10:11] sc1
	global_store_dword v2, v136, s[10:11] offset:256 sc1
	v_mul_f32_e32 v5, v6, v136
	v_mul_f32_e32 v7, v6, v135
	v_fma_f32 v5, v4, v135, -v5
	v_fma_f32 v7, v4, v136, v7
	v_add_f32_e32 v137, v5, v121
	v_add_f32_e32 v138, v7, v122
	global_store_dword v2, v137, s[10:11] offset:512 sc1
	global_store_dword v2, v138, s[10:11] offset:768 sc1
	v_mul_f32_e32 v5, v6, v138
	v_mul_f32_e32 v7, v6, v137
	v_fma_f32 v5, v4, v137, -v5
	v_fma_f32 v7, v4, v138, v7
	v_add_f32_e32 v135, v5, v123
	v_add_f32_e32 v136, v7, v124
	global_store_dword v2, v135, s[10:11] offset:1024 sc1
	global_store_dword v2, v136, s[10:11] offset:1280 sc1
	v_mul_f32_e32 v5, v6, v136
	v_mul_f32_e32 v7, v6, v135
	v_fma_f32 v5, v4, v135, -v5
	v_fma_f32 v7, v4, v136, v7
	v_add_f32_e32 v137, v5, v125
	v_add_f32_e32 v138, v7, v126
	global_store_dword v2, v137, s[10:11] offset:1536 sc1
	global_store_dword v2, v138, s[10:11] offset:1792 sc1
	v_mul_f32_e32 v5, v6, v138
	v_mul_f32_e32 v7, v6, v137
	v_fma_f32 v5, v4, v137, -v5
	v_fma_f32 v7, v4, v138, v7
	v_add_f32_e32 v135, v5, v127
	v_add_f32_e32 v136, v7, v128
	global_store_dword v2, v135, s[10:11] offset:2048 sc1
	global_store_dword v2, v136, s[10:11] offset:2304 sc1
	v_mul_f32_e32 v5, v6, v136
	v_mul_f32_e32 v7, v6, v135
	v_fma_f32 v5, v4, v135, -v5
	v_fma_f32 v7, v4, v136, v7
	v_add_f32_e32 v137, v5, v129
	v_add_f32_e32 v138, v7, v130
	global_store_dword v2, v137, s[10:11] offset:2560 sc1
	global_store_dword v2, v138, s[10:11] offset:2816 sc1
	v_mul_f32_e32 v5, v6, v138
	v_mul_f32_e32 v7, v6, v137
	v_fma_f32 v5, v4, v137, -v5
	v_fma_f32 v7, v4, v138, v7
	v_add_f32_e32 v135, v5, v131
	v_add_f32_e32 v136, v7, v132
	global_store_dword v2, v135, s[10:11] offset:3072 sc1
	global_store_dword v2, v136, s[10:11] offset:3328 sc1
	v_mul_f32_e32 v5, v6, v136
	v_mul_f32_e32 v7, v6, v135
	v_fma_f32 v5, v4, v135, -v5
	v_fma_f32 v7, v4, v136, v7
	v_add_f32_e32 v137, v5, v133
	v_add_f32_e32 v138, v7, v134
	global_store_dword v2, v137, s[10:11] offset:3584 sc1
	global_store_dword v2, v138, s[10:11] offset:3840 sc1
	v_readlane_b32 s92, v254, 47
	s_add_i32 s37, s37, 1
	s_add_i32 s39, s39, s92
	s_cmp_lt_i32 s39, 32
	v_readlane_b32 s93, v254, 48
	s_cbranch_scc0 .LBB0_561
	v_readlane_b32 s48, v254, 54
	v_readlane_b32 s49, v254, 55
	s_branch .LBB0_557

; __device__ __forceinline__ void hgrn_scan(const PA& a, int task, int lane) {
;     float* HU = (float*)(a.ws + WS_HU); const float* HA = (const float*)(a.ws + WS_HA);
;     const int bh = task >> 6, r = task & 63, dk = 16 * (r >> 4) + 4 * (r & 3) + (lane & 3);
;     float* up = HU + (size_t)(bh * 64) * 4096 + (size_t)r * 64 + lane; const float* ap = HA + (size_t)(bh * 64) * 64 + dk;
;     float S = 0.f;
; #pragma unroll 1
;     for (int c0 = 0; c0 < 64; c0 += 32) {
;         float u[32], av[32];
; #pragma unroll
;         for (int i = 0; i < 32; ++i) { u[i] = up[(size_t)(c0 + i) * 4096]; av[i] = ap[(size_t)(c0 + i) * 64]; }
; #pragma unroll
;         for (int i = 0; i < 32; ++i) { __hip_atomic_store(up + (size_t)(c0 + i) * 4096, S, __ATOMIC_RELAXED, __HIP_MEMORY_SCOPE_AGENT); S = av[i] * S + u[i]; }
;     }
; }
; __global__ void __launch_bounds__(NWAVES * 64, 2) hymba_fwd(Args args) {
;     ...
;               if (wave < 2) { for (int t2 = wave * G + vcu; t2 < 512; t2 += 2 * G) { hgrn_scan(pa, t2, lane); ++ndone; } }
.LBB0_566:
	s_lshl_b32 s0, s2, 2
	v_and_or_b32 v0, s2, 48, v6
	v_and_or_b32 v2, s0, 12, v0
	s_and_b32 s0, s2, 0xffffffc0
	s_ashr_i32 s1, s0, 31
	s_lshl_b64 s[8:9], s[0:1], 14
	s_add_u32 s3, s89, s8
	s_addc_u32 s9, s25, s9
	s_lshl_b32 s8, s2, 8
	s_and_b32 s8, s8, 0x3f00
	s_add_u32 s8, s3, s8
	s_addc_u32 s9, s9, 0
	s_lshl_b64 s[0:1], s[0:1], 8
	s_add_u32 s0, s39, s0
	s_addc_u32 s1, s54, s1
	v_lshlrev_b32_e32 v2, 2, v2
	s_mov_b64 s[10:11], s[8:9]
	global_load_dword v8, v220, s[10:11]
	global_load_dword v9, v2, s[0:1]
	s_add_u32 s10, s10, 0x4000
	s_addc_u32 s11, s11, 0
	global_load_dword v10, v220, s[10:11]
	global_load_dword v11, v2, s[0:1] offset:256
	s_add_u32 s10, s10, 0x4000
	s_addc_u32 s11, s11, 0
	global_load_dword v12, v220, s[10:11]
	global_load_dword v13, v2, s[0:1] offset:512
	s_add_u32 s10, s10, 0x4000
	s_addc_u32 s11, s11, 0
	global_load_dword v14, v220, s[10:11]
	global_load_dword v15, v2, s[0:1] offset:768
	s_add_u32 s10, s10, 0x4000
	s_addc_u32 s11, s11, 0
	global_load_dword v16, v220, s[10:11]
	global_load_dword v17, v2, s[0:1] offset:1024
	s_add_u32 s10, s10, 0x4000
	s_addc_u32 s11, s11, 0
	global_load_dword v18, v220, s[10:11]
	global_load_dword v19, v2, s[0:1] offset:1280
	s_add_u32 s10, s10, 0x4000
	s_addc_u32 s11, s11, 0
	global_load_dword v20, v220, s[10:11]
	global_load_dword v21, v2, s[0:1] offset:1536
	s_add_u32 s10, s10, 0x4000
	s_addc_u32 s11, s11, 0
	global_load_dword v22, v220, s[10:11]
	global_load_dword v23, v2, s[0:1] offset:1792
	s_add_u32 s10, s10, 0x4000
	s_addc_u32 s11, s11, 0
	global_load_dword v24, v220, s[10:11]
	global_load_dword v25, v2, s[0:1] offset:2048
	s_add_u32 s10, s10, 0x4000
	s_addc_u32 s11, s11, 0
	global_load_dword v26, v220, s[10:11]
	global_load_dword v27, v2, s[0:1] offset:2304
	s_add_u32 s10, s10, 0x4000
	s_addc_u32 s11, s11, 0
	global_load_dword v28, v220, s[10:11]
	global_load_dword v29, v2, s[0:1] offset:2560
	s_add_u32 s10, s10, 0x4000
	s_addc_u32 s11, s11, 0
	global_load_dword v30, v220, s[10:11]
	global_load_dword v31, v2, s[0:1] offset:2816
	s_add_u32 s10, s10, 0x4000
	s_addc_u32 s11, s11, 0
	global_load_dword v32, v220, s[10:11]
	global_load_dword v33, v2, s[0:1] offset:3072
	s_add_u32 s10, s10, 0x4000
	s_addc_u32 s11, s11, 0
	global_load_dword v34, v220, s[10:11]
	global_load_dword v35, v2, s[0:1] offset:3328
	s_add_u32 s10, s10, 0x4000
	s_addc_u32 s11, s11, 0
	global_load_dword v36, v220, s[10:11]
	global_load_dword v37, v2, s[0:1] offset:3584
	s_add_u32 s10, s10, 0x4000
	s_addc_u32 s11, s11, 0
	global_load_dword v38, v220, s[10:11]
	global_load_dword v39, v2, s[0:1] offset:3840
	s_add_u32 s10, s10, 0x4000
	s_addc_u32 s11, s11, 0
	s_add_u32 s0, s0, 0x1000
	s_addc_u32 s1, s1, 0
	global_load_dword v40, v220, s[10:11]
	global_load_dword v41, v2, s[0:1]
	s_add_u32 s10, s10, 0x4000
	s_addc_u32 s11, s11, 0
	global_load_dword v42, v220, s[10:11]
	global_load_dword v43, v2, s[0:1] offset:256
	s_add_u32 s10, s10, 0x4000
	s_addc_u32 s11, s11, 0
	global_load_dword v44, v220, s[10:11]
	global_load_dword v45, v2, s[0:1] offset:512
	s_add_u32 s10, s10, 0x4000
	s_addc_u32 s11, s11, 0
	global_load_dword v46, v220, s[10:11]
	global_load_dword v47, v2, s[0:1] offset:768
	s_add_u32 s10, s10, 0x4000
	s_addc_u32 s11, s11, 0
	global_load_dword v48, v220, s[10:11]
	global_load_dword v49, v2, s[0:1] offset:1024
	s_add_u32 s10, s10, 0x4000
	s_addc_u32 s11, s11, 0
	global_load_dword v50, v220, s[10:11]
	global_load_dword v51, v2, s[0:1] offset:1280
	s_add_u32 s10, s10, 0x4000
	s_addc_u32 s11, s11, 0
	global_load_dword v52, v220, s[10:11]
	global_load_dword v53, v2, s[0:1] offset:1536
	s_add_u32 s10, s10, 0x4000
	s_addc_u32 s11, s11, 0
	global_load_dword v54, v220, s[10:11]
	global_load_dword v55, v2, s[0:1] offset:1792
	s_add_u32 s10, s10, 0x4000
	s_addc_u32 s11, s11, 0
	global_load_dword v56, v220, s[10:11]
	global_load_dword v57, v2, s[0:1] offset:2048
	s_add_u32 s10, s10, 0x4000
	s_addc_u32 s11, s11, 0
	global_load_dword v58, v220, s[10:11]
	global_load_dword v59, v2, s[0:1] offset:2304
	s_add_u32 s10, s10, 0x4000
	s_addc_u32 s11, s11, 0
	global_load_dword v60, v220, s[10:11]
	global_load_dword v61, v2, s[0:1] offset:2560
	s_add_u32 s10, s10, 0x4000
	s_addc_u32 s11, s11, 0
	global_load_dword v62, v220, s[10:11]
	global_load_dword v63, v2, s[0:1] offset:2816
	s_add_u32 s10, s10, 0x4000
	s_addc_u32 s11, s11, 0
	global_load_dword v64, v220, s[10:11]
	global_load_dword v65, v2, s[0:1] offset:3072
	s_add_u32 s10, s10, 0x4000
	s_addc_u32 s11, s11, 0
	global_load_dword v66, v220, s[10:11]
	global_load_dword v67, v2, s[0:1] offset:3328
	s_add_u32 s10, s10, 0x4000
	s_addc_u32 s11, s11, 0
	global_load_dword v68, v220, s[10:11]
	global_load_dword v69, v2, s[0:1] offset:3584
	s_add_u32 s10, s10, 0x4000
	s_addc_u32 s11, s11, 0
	global_load_dword v70, v220, s[10:11]
	global_load_dword v71, v2, s[0:1] offset:3840
	s_add_u32 s10, s10, 0x4000
	s_addc_u32 s11, s11, 0
	s_add_u32 s0, s0, 0x1000
	s_addc_u32 s1, s1, 0
	global_load_dword v72, v220, s[10:11]
	global_load_dword v73, v2, s[0:1]
	s_add_u32 s10, s10, 0x4000
	s_addc_u32 s11, s11, 0
	global_load_dword v74, v220, s[10:11]
	global_load_dword v75, v2, s[0:1] offset:256
	s_add_u32 s10, s10, 0x4000
	s_addc_u32 s11, s11, 0
	global_load_dword v76, v220, s[10:11]
	global_load_dword v77, v2, s[0:1] offset:512
	s_add_u32 s10, s10, 0x4000
	s_addc_u32 s11, s11, 0
	global_load_dword v78, v220, s[10:11]
	global_load_dword v79, v2, s[0:1] offset:768
	s_add_u32 s10, s10, 0x4000
	s_addc_u32 s11, s11, 0
	global_load_dword v80, v220, s[10:11]
	global_load_dword v81, v2, s[0:1] offset:1024
	s_add_u32 s10, s10, 0x4000
	s_addc_u32 s11, s11, 0
	global_load_dword v82, v220, s[10:11]
; __device__ __forceinline__ void hgrn_scan(const PA& a, int task, int lane) {
;     ...
;         for (int i = 0; i < 32; ++i) { u[i] = up[(size_t)(c0 + i) * 4096]; av[i] = ap[(size_t)(c0 + i) * 64]; }
; #pragma unroll
;         for (int i = 0; i < 32; ++i) { __hip_atomic_store(up + (size_t)(c0 + i) * 4096, S, __ATOMIC_RELAXED, __HIP_MEMORY_SCOPE_AGENT); S = av[i] * S + u[i]; }
	global_load_dword v83, v2, s[0:1] offset:1280
	s_add_u32 s10, s10, 0x4000
	s_addc_u32 s11, s11, 0
	global_load_dword v84, v220, s[10:11]
	global_load_dword v85, v2, s[0:1] offset:1536
	s_add_u32 s10, s10, 0x4000
	s_addc_u32 s11, s11, 0
	global_load_dword v86, v220, s[10:11]
	global_load_dword v87, v2, s[0:1] offset:1792
	s_add_u32 s10, s10, 0x4000
	s_addc_u32 s11, s11, 0
	global_load_dword v88, v220, s[10:11]
	global_load_dword v89, v2, s[0:1] offset:2048
	s_add_u32 s10, s10, 0x4000
	s_addc_u32 s11, s11, 0
	global_load_dword v90, v220, s[10:11]
	global_load_dword v91, v2, s[0:1] offset:2304
	s_add_u32 s10, s10, 0x4000
	s_addc_u32 s11, s11, 0
	global_load_dword v92, v220, s[10:11]
	global_load_dword v93, v2, s[0:1] offset:2560
	s_add_u32 s10, s10, 0x4000
	s_addc_u32 s11, s11, 0
	global_load_dword v94, v220, s[10:11]
	global_load_dword v95, v2, s[0:1] offset:2816
	s_add_u32 s10, s10, 0x4000
	s_addc_u32 s11, s11, 0
	global_load_dword v97, v220, s[10:11]
	global_load_dword v98, v2, s[0:1] offset:3072
	s_add_u32 s10, s10, 0x4000
	s_addc_u32 s11, s11, 0
	global_load_dword v99, v220, s[10:11]
	global_load_dword v100, v2, s[0:1] offset:3328
	s_add_u32 s10, s10, 0x4000
	s_addc_u32 s11, s11, 0
	global_load_dword v101, v220, s[10:11]
	global_load_dword v102, v2, s[0:1] offset:3584
	s_add_u32 s10, s10, 0x4000
	s_addc_u32 s11, s11, 0
	global_load_dword v103, v220, s[10:11]
	global_load_dword v104, v2, s[0:1] offset:3840
	s_add_u32 s10, s10, 0x4000
	s_addc_u32 s11, s11, 0
	s_add_u32 s0, s0, 0x1000
	s_addc_u32 s1, s1, 0
	global_load_dword v105, v220, s[10:11]
	global_load_dword v106, v2, s[0:1]
	s_add_u32 s10, s10, 0x4000
	s_addc_u32 s11, s11, 0
	global_load_dword v107, v220, s[10:11]
	global_load_dword v108, v2, s[0:1] offset:256
	s_add_u32 s10, s10, 0x4000
	s_addc_u32 s11, s11, 0
	global_load_dword v109, v220, s[10:11]
	global_load_dword v110, v2, s[0:1] offset:512
	s_add_u32 s10, s10, 0x4000
	s_addc_u32 s11, s11, 0
	global_load_dword v111, v220, s[10:11]
	global_load_dword v112, v2, s[0:1] offset:768
	s_add_u32 s10, s10, 0x4000
	s_addc_u32 s11, s11, 0
	global_load_dword v113, v220, s[10:11]
	global_load_dword v114, v2, s[0:1] offset:1024
	s_add_u32 s10, s10, 0x4000
	s_addc_u32 s11, s11, 0
	global_load_dword v115, v220, s[10:11]
	global_load_dword v116, v2, s[0:1] offset:1280
	s_add_u32 s10, s10, 0x4000
	s_addc_u32 s11, s11, 0
	global_load_dword v117, v220, s[10:11]
	global_load_dword v118, v2, s[0:1] offset:1536
	s_add_u32 s10, s10, 0x4000
	s_addc_u32 s11, s11, 0
	global_load_dword v119, v220, s[10:11]
	global_load_dword v120, v2, s[0:1] offset:1792
	s_add_u32 s10, s10, 0x4000
	s_addc_u32 s11, s11, 0
	global_load_dword v121, v220, s[10:11]
	global_load_dword v122, v2, s[0:1] offset:2048
	s_add_u32 s10, s10, 0x4000
	s_addc_u32 s11, s11, 0
	global_load_dword v123, v220, s[10:11]
	global_load_dword v124, v2, s[0:1] offset:2304
	s_add_u32 s10, s10, 0x4000
	s_addc_u32 s11, s11, 0
	global_load_dword v125, v220, s[10:11]
	global_load_dword v126, v2, s[0:1] offset:2560
	s_add_u32 s10, s10, 0x4000
	s_addc_u32 s11, s11, 0
	global_load_dword v127, v220, s[10:11]
	global_load_dword v128, v2, s[0:1] offset:2816
	s_add_u32 s10, s10, 0x4000
	s_addc_u32 s11, s11, 0
	global_load_dword v129, v220, s[10:11]
	global_load_dword v130, v2, s[0:1] offset:3072
	s_add_u32 s10, s10, 0x4000
	s_addc_u32 s11, s11, 0
	global_load_dword v131, v220, s[10:11]
	global_load_dword v132, v2, s[0:1] offset:3328
	s_add_u32 s10, s10, 0x4000
	s_addc_u32 s11, s11, 0
	global_load_dword v133, v220, s[10:11]
	global_load_dword v134, v2, s[0:1] offset:3584
	s_add_u32 s10, s10, 0x4000
	s_addc_u32 s11, s11, 0
	v_mov_b32_e32 v135, 0
	global_store_dword v220, v135, s[8:9] sc1
	s_waitcnt vmcnt(63)
	v_fma_f32 v136, v9, v135, v8
	s_add_u32 s8, s8, 0x4000
	s_addc_u32 s9, s9, 0
	global_store_dword v220, v136, s[8:9] sc1
	s_waitcnt vmcnt(63)
	v_fma_f32 v135, v11, v136, v10
	s_add_u32 s8, s8, 0x4000
	s_addc_u32 s9, s9, 0
	global_store_dword v220, v135, s[8:9] sc1
	s_waitcnt vmcnt(63)
	v_fma_f32 v136, v13, v135, v12
	s_add_u32 s8, s8, 0x4000
	s_addc_u32 s9, s9, 0
	global_store_dword v220, v136, s[8:9] sc1
	s_waitcnt vmcnt(63)
	v_fma_f32 v135, v15, v136, v14
	s_add_u32 s8, s8, 0x4000
	s_addc_u32 s9, s9, 0
	global_store_dword v220, v135, s[8:9] sc1
	s_waitcnt vmcnt(63)
	v_fma_f32 v136, v17, v135, v16
	s_add_u32 s8, s8, 0x4000
	s_addc_u32 s9, s9, 0
	global_store_dword v220, v136, s[8:9] sc1
	s_waitcnt vmcnt(63)
	v_fma_f32 v135, v19, v136, v18
	s_add_u32 s8, s8, 0x4000
	s_addc_u32 s9, s9, 0
	global_store_dword v220, v135, s[8:9] sc1
	s_waitcnt vmcnt(63)
	v_fma_f32 v136, v21, v135, v20
	s_add_u32 s8, s8, 0x4000
	s_addc_u32 s9, s9, 0
	global_store_dword v220, v136, s[8:9] sc1
	s_waitcnt vmcnt(63)
	v_fma_f32 v135, v23, v136, v22
	s_add_u32 s8, s8, 0x4000
	s_addc_u32 s9, s9, 0
	global_store_dword v220, v135, s[8:9] sc1
	s_waitcnt vmcnt(63)
	v_fma_f32 v136, v25, v135, v24
	s_add_u32 s8, s8, 0x4000
	s_addc_u32 s9, s9, 0
	global_store_dword v220, v136, s[8:9] sc1
	s_waitcnt vmcnt(63)
	v_fma_f32 v135, v27, v136, v26
	s_add_u32 s8, s8, 0x4000
	s_addc_u32 s9, s9, 0
	global_store_dword v220, v135, s[8:9] sc1
	s_waitcnt vmcnt(63)
	v_fma_f32 v136, v29, v135, v28
	s_add_u32 s8, s8, 0x4000
	s_addc_u32 s9, s9, 0
	global_store_dword v220, v136, s[8:9] sc1
	s_waitcnt vmcnt(63)
	v_fma_f32 v135, v31, v136, v30
	s_add_u32 s8, s8, 0x4000
	s_addc_u32 s9, s9, 0
	global_store_dword v220, v135, s[8:9] sc1
	s_waitcnt vmcnt(63)
	v_fma_f32 v136, v33, v135, v32
	s_add_u32 s8, s8, 0x4000
	s_addc_u32 s9, s9, 0
	global_store_dword v220, v136, s[8:9] sc1
	s_waitcnt vmcnt(63)
; __device__ __forceinline__ void hgrn_scan(const PA& a, int task, int lane) {
;     ...
;         for (int i = 0; i < 32; ++i) { __hip_atomic_store(up + (size_t)(c0 + i) * 4096, S, __ATOMIC_RELAXED, __HIP_MEMORY_SCOPE_AGENT); S = av[i] * S + u[i]; }
	v_fma_f32 v135, v35, v136, v34
	s_add_u32 s8, s8, 0x4000
	s_addc_u32 s9, s9, 0
	global_store_dword v220, v135, s[8:9] sc1
	s_waitcnt vmcnt(63)
	v_fma_f32 v136, v37, v135, v36
	s_add_u32 s8, s8, 0x4000
	s_addc_u32 s9, s9, 0
	global_store_dword v220, v136, s[8:9] sc1
	s_waitcnt vmcnt(63)
	v_fma_f32 v135, v39, v136, v38
	s_add_u32 s8, s8, 0x4000
	s_addc_u32 s9, s9, 0
	global_store_dword v220, v135, s[8:9] sc1
	s_waitcnt vmcnt(63)
	v_fma_f32 v136, v41, v135, v40
	s_add_u32 s8, s8, 0x4000
	s_addc_u32 s9, s9, 0
	global_store_dword v220, v136, s[8:9] sc1
	s_waitcnt vmcnt(63)
	v_fma_f32 v135, v43, v136, v42
	s_add_u32 s8, s8, 0x4000
	s_addc_u32 s9, s9, 0
	global_store_dword v220, v135, s[8:9] sc1
	s_waitcnt vmcnt(63)
	v_fma_f32 v136, v45, v135, v44
	s_add_u32 s8, s8, 0x4000
	s_addc_u32 s9, s9, 0
	global_store_dword v220, v136, s[8:9] sc1
	s_waitcnt vmcnt(63)
	v_fma_f32 v135, v47, v136, v46
	s_add_u32 s8, s8, 0x4000
	s_addc_u32 s9, s9, 0
	global_store_dword v220, v135, s[8:9] sc1
	s_waitcnt vmcnt(63)
	v_fma_f32 v136, v49, v135, v48
	s_add_u32 s8, s8, 0x4000
	s_addc_u32 s9, s9, 0
	global_store_dword v220, v136, s[8:9] sc1
	s_waitcnt vmcnt(63)
	v_fma_f32 v135, v51, v136, v50
	s_add_u32 s8, s8, 0x4000
	s_addc_u32 s9, s9, 0
	global_store_dword v220, v135, s[8:9] sc1
	s_waitcnt vmcnt(63)
	v_fma_f32 v136, v53, v135, v52
	s_add_u32 s8, s8, 0x4000
	s_addc_u32 s9, s9, 0
	global_store_dword v220, v136, s[8:9] sc1
	s_waitcnt vmcnt(63)
	v_fma_f32 v135, v55, v136, v54
	s_add_u32 s8, s8, 0x4000
	s_addc_u32 s9, s9, 0
	global_store_dword v220, v135, s[8:9] sc1
	s_waitcnt vmcnt(63)
	v_fma_f32 v136, v57, v135, v56
	s_add_u32 s8, s8, 0x4000
	s_addc_u32 s9, s9, 0
	global_store_dword v220, v136, s[8:9] sc1
	s_waitcnt vmcnt(63)
	v_fma_f32 v135, v59, v136, v58
	s_add_u32 s8, s8, 0x4000
	s_addc_u32 s9, s9, 0
	global_store_dword v220, v135, s[8:9] sc1
	s_waitcnt vmcnt(63)
	v_fma_f32 v136, v61, v135, v60
	s_add_u32 s8, s8, 0x4000
	s_addc_u32 s9, s9, 0
	global_store_dword v220, v136, s[8:9] sc1
	s_waitcnt vmcnt(63)
	v_fma_f32 v135, v63, v136, v62
	s_add_u32 s8, s8, 0x4000
	s_addc_u32 s9, s9, 0
	global_store_dword v220, v135, s[8:9] sc1
	s_waitcnt vmcnt(63)
	v_fma_f32 v136, v65, v135, v64
	s_add_u32 s8, s8, 0x4000
	s_addc_u32 s9, s9, 0
	global_store_dword v220, v136, s[8:9] sc1
	s_waitcnt vmcnt(63)
	v_fma_f32 v135, v67, v136, v66
	s_add_u32 s8, s8, 0x4000
	s_addc_u32 s9, s9, 0
	global_store_dword v220, v135, s[8:9] sc1
	s_waitcnt vmcnt(63)
	v_fma_f32 v136, v69, v135, v68
	s_add_u32 s8, s8, 0x4000
	s_addc_u32 s9, s9, 0
	global_store_dword v220, v136, s[8:9] sc1
	s_waitcnt vmcnt(63)
	v_fma_f32 v135, v71, v136, v70
	s_add_u32 s8, s8, 0x4000
	s_addc_u32 s9, s9, 0
	global_store_dword v220, v135, s[8:9] sc1
	s_waitcnt vmcnt(63)
	v_fma_f32 v136, v73, v135, v72
	s_add_u32 s8, s8, 0x4000
	s_addc_u32 s9, s9, 0
	global_store_dword v220, v136, s[8:9] sc1
	s_waitcnt vmcnt(63)
	v_fma_f32 v135, v75, v136, v74
	s_add_u32 s8, s8, 0x4000
	s_addc_u32 s9, s9, 0
	global_store_dword v220, v135, s[8:9] sc1
	s_waitcnt vmcnt(63)
	v_fma_f32 v136, v77, v135, v76
	s_add_u32 s8, s8, 0x4000
	s_addc_u32 s9, s9, 0
	global_store_dword v220, v136, s[8:9] sc1
	s_waitcnt vmcnt(63)
	v_fma_f32 v135, v79, v136, v78
	s_add_u32 s8, s8, 0x4000
	s_addc_u32 s9, s9, 0
	global_store_dword v220, v135, s[8:9] sc1
	s_waitcnt vmcnt(63)
	v_fma_f32 v136, v81, v135, v80
	s_add_u32 s8, s8, 0x4000
	s_addc_u32 s9, s9, 0
	global_store_dword v220, v136, s[8:9] sc1
	s_waitcnt vmcnt(63)
	v_fma_f32 v135, v83, v136, v82
	s_add_u32 s8, s8, 0x4000
	s_addc_u32 s9, s9, 0
	global_store_dword v220, v135, s[8:9] sc1
	s_waitcnt vmcnt(63)
; __device__ __forceinline__ void hgrn_scan(const PA& a, int task, int lane) {
;     ...
;         for (int i = 0; i < 32; ++i) { __hip_atomic_store(up + (size_t)(c0 + i) * 4096, S, __ATOMIC_RELAXED, __HIP_MEMORY_SCOPE_AGENT); S = av[i] * S + u[i]; }
; __global__ void __launch_bounds__(NWAVES * 64, 2) hymba_fwd(Args args) {
;     ...
;               if (wave < 2) { for (int t2 = wave * G + vcu; t2 < 512; t2 += 2 * G) { hgrn_scan(pa, t2, lane); ++ndone; } }
	v_fma_f32 v136, v85, v135, v84
	s_add_u32 s8, s8, 0x4000
	s_addc_u32 s9, s9, 0
	global_store_dword v220, v136, s[8:9] sc1
	s_waitcnt vmcnt(63)
	v_fma_f32 v135, v87, v136, v86
	s_add_u32 s8, s8, 0x4000
	s_addc_u32 s9, s9, 0
	global_store_dword v220, v135, s[8:9] sc1
	s_waitcnt vmcnt(63)
	v_fma_f32 v136, v89, v135, v88
	s_add_u32 s8, s8, 0x4000
	s_addc_u32 s9, s9, 0
	global_store_dword v220, v136, s[8:9] sc1
	s_waitcnt vmcnt(63)
	v_fma_f32 v135, v91, v136, v90
	s_add_u32 s8, s8, 0x4000
	s_addc_u32 s9, s9, 0
	global_store_dword v220, v135, s[8:9] sc1
	s_waitcnt vmcnt(63)
	v_fma_f32 v136, v93, v135, v92
	s_add_u32 s8, s8, 0x4000
	s_addc_u32 s9, s9, 0
	global_store_dword v220, v136, s[8:9] sc1
	s_waitcnt vmcnt(63)
	v_fma_f32 v135, v95, v136, v94
	s_add_u32 s8, s8, 0x4000
	s_addc_u32 s9, s9, 0
	global_store_dword v220, v135, s[8:9] sc1
	s_waitcnt vmcnt(63)
	v_fma_f32 v136, v98, v135, v97
	s_add_u32 s8, s8, 0x4000
	s_addc_u32 s9, s9, 0
	global_store_dword v220, v136, s[8:9] sc1
	s_waitcnt vmcnt(63)
	v_fma_f32 v135, v100, v136, v99
	s_add_u32 s8, s8, 0x4000
	s_addc_u32 s9, s9, 0
	global_store_dword v220, v135, s[8:9] sc1
	s_waitcnt vmcnt(63)
	v_fma_f32 v136, v102, v135, v101
	s_add_u32 s8, s8, 0x4000
	s_addc_u32 s9, s9, 0
	global_store_dword v220, v136, s[8:9] sc1
	s_waitcnt vmcnt(63)
	v_fma_f32 v135, v104, v136, v103
	s_add_u32 s8, s8, 0x4000
	s_addc_u32 s9, s9, 0
	global_store_dword v220, v135, s[8:9] sc1
	s_waitcnt vmcnt(63)
	v_fma_f32 v136, v106, v135, v105
	s_add_u32 s8, s8, 0x4000
	s_addc_u32 s9, s9, 0
	global_store_dword v220, v136, s[8:9] sc1
	s_waitcnt vmcnt(63)
	v_fma_f32 v135, v108, v136, v107
	s_add_u32 s8, s8, 0x4000
	s_addc_u32 s9, s9, 0
	global_store_dword v220, v135, s[8:9] sc1
	s_waitcnt vmcnt(63)
	v_fma_f32 v136, v110, v135, v109
	s_add_u32 s8, s8, 0x4000
	s_addc_u32 s9, s9, 0
	global_store_dword v220, v136, s[8:9] sc1
	s_waitcnt vmcnt(63)
	v_fma_f32 v135, v112, v136, v111
	s_add_u32 s8, s8, 0x4000
	s_addc_u32 s9, s9, 0
	global_store_dword v220, v135, s[8:9] sc1
	s_waitcnt vmcnt(63)
	v_fma_f32 v136, v114, v135, v113
	s_add_u32 s8, s8, 0x4000
	s_addc_u32 s9, s9, 0
	global_store_dword v220, v136, s[8:9] sc1
	s_waitcnt vmcnt(63)
	v_fma_f32 v135, v116, v136, v115
	s_add_u32 s8, s8, 0x4000
	s_addc_u32 s9, s9, 0
	global_store_dword v220, v135, s[8:9] sc1
	s_waitcnt vmcnt(63)
	v_fma_f32 v136, v118, v135, v117
	s_add_u32 s8, s8, 0x4000
	s_addc_u32 s9, s9, 0
	global_store_dword v220, v136, s[8:9] sc1
	s_waitcnt vmcnt(63)
	v_fma_f32 v135, v120, v136, v119
	s_add_u32 s8, s8, 0x4000
	s_addc_u32 s9, s9, 0
	global_store_dword v220, v135, s[8:9] sc1
	s_waitcnt vmcnt(63)
	v_fma_f32 v136, v122, v135, v121
	s_add_u32 s8, s8, 0x4000
	s_addc_u32 s9, s9, 0
	global_store_dword v220, v136, s[8:9] sc1
	s_waitcnt vmcnt(63)
	v_fma_f32 v135, v124, v136, v123
	s_add_u32 s8, s8, 0x4000
	s_addc_u32 s9, s9, 0
	global_store_dword v220, v135, s[8:9] sc1
	s_waitcnt vmcnt(63)
	v_fma_f32 v136, v126, v135, v125
	s_add_u32 s8, s8, 0x4000
	s_addc_u32 s9, s9, 0
	global_store_dword v220, v136, s[8:9] sc1
	s_waitcnt vmcnt(63)
	v_fma_f32 v135, v128, v136, v127
	s_add_u32 s8, s8, 0x4000
	s_addc_u32 s9, s9, 0
	global_store_dword v220, v135, s[8:9] sc1
	s_waitcnt vmcnt(63)
	v_fma_f32 v136, v130, v135, v129
	s_add_u32 s8, s8, 0x4000
	s_addc_u32 s9, s9, 0
	global_store_dword v220, v136, s[8:9] sc1
	s_waitcnt vmcnt(63)
	v_fma_f32 v135, v132, v136, v131
	s_add_u32 s8, s8, 0x4000
	s_addc_u32 s9, s9, 0
	global_store_dword v220, v135, s[8:9] sc1
	s_waitcnt vmcnt(63)
	v_fma_f32 v136, v134, v135, v133
	s_add_u32 s8, s8, 0x4000
	s_addc_u32 s9, s9, 0
	global_store_dword v220, v136, s[8:9] sc1
	s_add_i32 s37, s37, 1
	s_add_i32 s2, s2, s12
	s_cmpk_gt_i32 s2, 0x1ff
	s_cbranch_scc0 .LBB0_566
